# prep weight transposes: a workgroup's eight waves take eight adjacent 64-column tiles of the same k-rows (2 KB contiguous reads per row)
# speedup vs baseline: 1.0153x; 1.0036x over previous
.LBB0_14:
	s_or_saveexec_b64 s[30:31], s[30:31]
	v_mov_b64_e32 v[78:79], 0
	v_mov_b64_e32 v[62:63], 0x80
	s_xor_b64 exec, exec, s[30:31]
	s_cbranch_execz .LBB0_16
	v_add_u32_e32 v2, 0xfffff400, v126
	v_bfe_u32 v8, v2, 3, 5
	v_and_b32_e32 v4, 7, v2
	v_lshrrev_b32_e32 v2, 8, v2
	v_lshl_or_b32 v4, v2, 3, v4
	v_lshlrev_b32_e32 v2, 8, v8
	v_mov_b32_e32 v3, v71
	s_waitcnt lgkmcnt(0)
	v_lshl_add_u64 v[6:7], s[44:45], 0, v[2:3]
	v_lshl_add_u64 v[6:7], v[6:7], 0, s[10:11]
	v_lshl_add_u64 v[2:3], s[42:43], 0, v[2:3]
	v_cmp_gt_u32_e32 vcc, 16, v8
	v_mov_b32_e32 v5, v71
	v_mov_b64_e32 v[62:63], 0x800
	v_cndmask_b32_e32 v79, v7, v3, vcc
	v_cndmask_b32_e32 v78, v6, v2, vcc
	v_lshlrev_b32_e32 v2, 19, v8
	v_mov_b32_e32 v3, v71
	v_lshl_add_u64 v[2:3], s[46:47], 0, v[2:3]
	v_lshlrev_b32_e32 v6, 6, v4
	v_mov_b32_e32 v7, v71
	v_lshlrev_b64 v[4:5], 18, v[4:5]
	v_lshl_add_u64 v[2:3], v[6:7], 2, v[2:3]
	v_lshl_add_u64 v[4:5], s[56:57], 0, v[4:5]
	v_lshlrev_b32_e32 v6, 7, v8
	v_lshl_add_u64 v[76:77], v[4:5], 0, v[6:7]

.LBB0_17:
	s_or_saveexec_b64 s[28:29], s[28:29]
	v_mov_b64_e32 v[74:75], v[62:63]
	s_xor_b64 exec, exec, s[28:29]
	s_cbranch_execz .LBB0_19
	v_and_b32_e32 v8, 7, v126
	v_lshrrev_b32_e32 v4, 8, v126
	v_lshlrev_b32_e32 v4, 9, v4
	v_lshl_or_b32 v4, v8, 6, v4
	v_bfe_u32 v8, v126, 3, 5
	v_cmp_lt_i32_e32 vcc, s86, v4
	v_mul_u32_u24_e32 v3, 0x60200, v8
	v_lshlrev_b32_e32 v6, 2, v3
	v_cndmask_b32_e64 v2, 0, 8, vcc
	v_or_b32_e32 v2, v2, v4
	v_mov_b32_e32 v7, v71
	v_ashrrev_i32_e32 v5, 31, v4
	s_waitcnt lgkmcnt(0)
	v_lshl_add_u64 v[6:7], s[16:17], 0, v[6:7]
	v_ashrrev_i32_e32 v3, 31, v2
	v_lshlrev_b64 v[4:5], 12, v[4:5]
	v_lshl_add_u64 v[2:3], v[2:3], 2, v[6:7]
	v_lshl_add_u64 v[4:5], s[54:55], 0, v[4:5]
	v_lshlrev_b32_e32 v6, 7, v8
	v_mov_b32_e32 v7, v71
	v_lshl_add_u64 v[76:77], v[4:5], 0, v[6:7]
	v_mov_b64_e32 v[74:75], 0x800
	v_mov_b64_e32 v[62:63], 0x1808
	v_mov_b64_e32 v[78:79], 0
